# P7 merge epilogue without the redundant canonicalising max before each clamp; sc1 write-through on the 16-byte epilogue stores of P1, P4 and P10 only
# baseline (speedup 1.0000x reference)
;     __device__ __forceinline__ void operator()(f32x4 (&acc)[2][2][4][2], const Unit& u, int wr, int wc, int fr, int fq) const {
;         const int row0 = u.pm * BM + wr * 64 + fr, col0 = u.pn * BM + wc * 32 + 8 * fq;
;         const bool last = (u.kind == 2);
;         const int koff = 5120 + u.kind * 2048, noff = last ? 0 : 2048;
; #pragma unroll
;         for (int ai = 0; ai < 2; ++ai)
; #pragma unroll
;             for (int m2 = 0; m2 < 2; ++m2) {
;                 u32x4 ga[2][2], gb[2][2];
; #pragma unroll
;                 for (int mm = 0; mm < 2; ++mm)
; #pragma unroll
;                     for (int bj = 0; bj < 2; ++bj) {
;                         const bf16_t* zp = Z + (size_t)(row0 + ai * HALF + (2 * m2 + mm) * 16) * NZ + koff + col0 + bj * HALF;
;                         ga[mm][bj] = *(const u32x4*)zp;
;                         gb[mm][bj] = *(const u32x4*)(zp + noff);
;                     }
; #pragma unroll
;                 for (int mm = 0; mm < 2; ++mm)
; #pragma unroll
;                     for (int bj = 0; bj < 2; ++bj) {
;                         const int m = 2 * m2 + mm;
;                         const u32x4 a4 = ga[mm][bj], b4 = gb[mm][bj];
;                         f32x4 g0 = (f32x4){bflo(a4.x), bfhi(a4.x), bflo(a4.y), bfhi(a4.y)}, g1 = (f32x4){bflo(a4.z), bfhi(a4.z), bflo(a4.w), bfhi(a4.w)};
;                         const f32x4 h0 = (f32x4){bflo(b4.x), bfhi(b4.x), bflo(b4.y), bfhi(b4.y)}, h1 = (f32x4){bflo(b4.z), bfhi(b4.z), bflo(b4.w), bfhi(b4.w)};
; #pragma unroll
;                         for (int j = 0; j < 4; ++j) {
;                             g0[j] = fmaxf(g0[j], 1e-6f) * (last ? 1.0f : __builtin_amdgcn_rcpf(fmaxf(h0[j], 1e-6f)));
;                             g1[j] = fmaxf(g1[j], 1e-6f) * (last ? 1.0f : __builtin_amdgcn_rcpf(fmaxf(h1[j], 1e-6f)));
;                         }
;                         acc[ai][bj][m][0] *= g0; acc[ai][bj][m][1] *= g1;
;                         if (last) {
;                             const f32x4 v0 = acc[ai][bj][m][0], v1 = acc[ai][bj][m][1];
;                             u32x4 w; w.x = cvt_pk_bf16(v0[0], v0[1]); w.y = cvt_pk_bf16(v0[2], v0[3]); w.z = cvt_pk_bf16(v1[0], v1[1]); w.w = cvt_pk_bf16(v1[2], v1[3]);
;                             *(u32x4*)(MB + (size_t)(row0 + ai * HALF + m * 16) * D + col0 + bj * HALF) = w;
;                         }
;                     }
.LBB0_824:
	s_lshl_b32 s4, s51, 11
	s_cmp_eq_u32 s51, 2
	s_cselect_b64 s[20:21], -1, 0
	s_and_b64 s[22:23], s[20:21], exec
	v_lshl_add_u32 v168, s0, 8, v153
	s_cselect_b32 s0, 0, 0x800
	s_ashr_i32 s5, s4, 31
	s_lshl_b64 s[4:5], s[4:5], 1
	s_add_u32 s22, s40, s4
	v_lshl_or_b32 v166, s52, 8, v182
	s_addc_u32 s23, s41, s5
	v_ashrrev_i32_e32 v167, 31, v166
	v_mov_b64_e32 v[128:129], s[22:23]
	v_mad_i64_i32 v[130:131], s[4:5], v168, s46, v[128:129]
	v_lshlrev_b64 v[170:171], 1, v[166:167]
	v_lshl_add_u64 v[130:131], v[130:131], 0, v[170:171]
	v_add_co_u32_e32 v132, vcc, s37, v130
	s_lshl_b32 s0, s0, 1
	s_nop 0
	v_addc_co_u32_e32 v133, vcc, 0, v131, vcc
	v_lshl_add_u64 v[130:131], v[130:131], 0, s[12:13]
	v_lshl_add_u64 v[136:137], v[130:131], 0, s[0:1]
	global_load_dwordx4 v[184:187], v[132:133], off offset:2048
	global_load_dwordx4 v[148:151], v[130:131], off offset:256
	global_load_dwordx4 v[188:191], v[136:137], off
	v_or_b32_e32 v172, 16, v168
	v_mad_i64_i32 v[128:129], s[4:5], v172, s46, v[128:129]
	v_lshl_add_u64 v[128:129], v[128:129], 0, v[170:171]
	v_lshl_add_u64 v[132:133], v[128:129], 0, s[12:13]
	v_add_co_u32_e32 v128, vcc, s37, v128
	v_lshl_add_u64 v[130:131], v[132:133], 0, s[0:1]
	s_nop 0
	v_addc_co_u32_e32 v129, vcc, 0, v129, vcc
	global_load_dwordx4 v[140:143], v[128:129], off offset:2048
	s_nop 0
	global_load_dwordx4 v[132:135], v[132:133], off offset:256
	s_nop 0
	global_load_dwordx4 v[144:147], v[136:137], off offset:256
	s_nop 0
	global_load_dwordx4 v[136:139], v[130:131], off
	s_nop 0
	global_load_dwordx4 v[128:131], v[130:131], off offset:256
	v_ashrrev_i32_e32 v169, 31, v168
	v_lshlrev_b64 v[174:175], 12, v[168:169]
	v_lshl_add_u64 v[174:175], s[58:59], 0, v[174:175]
	s_cmp_lg_u32 s51, 2
	v_lshl_add_u64 v[174:175], v[166:167], 1, v[174:175]
	s_waitcnt vmcnt(0)
	v_lshlrev_b32_e32 v169, 16, v184
	v_and_b32_e32 v173, 0xffff0000, v184
	v_lshlrev_b32_e32 v184, 16, v185
	v_and_b32_e32 v192, 0xffff0000, v185
	v_lshlrev_b32_e32 v185, 16, v186
	v_and_b32_e32 v186, 0xffff0000, v186
	v_lshlrev_b32_e32 v193, 16, v187
	v_and_b32_e32 v194, 0xffff0000, v187
	v_lshlrev_b32_e32 v187, 16, v188
	v_lshlrev_b32_e32 v195, 16, v189
	v_lshlrev_b32_e32 v196, 16, v190
	v_and_b32_e32 v190, 0xffff0000, v190
	v_max_f32_e32 v198, 0x358637bd, v186
	v_max_f32_e32 v186, v190, v190
	v_max_f32_e32 v190, 0x358637bd, v184
	v_max_f32_e32 v187, 0x358637bd, v187
	v_max_f32_e32 v184, 0x358637bd, v195
	v_rcp_f32_e32 v187, v187
	v_rcp_f32_e32 v184, v184
	v_and_b32_e32 v188, 0xffff0000, v188
	v_and_b32_e32 v189, 0xffff0000, v189
	v_max_f32_e32 v169, 0x358637bd, v169
	v_max_f32_e32 v196, 0x358637bd, v196
	v_max_f32_e32 v188, 0x358637bd, v188
	v_cndmask_b32_e64 v187, v187, 1.0, s[20:21]
	v_max_f32_e32 v186, 0x358637bd, v186
	v_rcp_f32_e32 v196, v196
	v_rcp_f32_e32 v188, v188
	v_cndmask_b32_e64 v199, v184, 1.0, s[20:21]
	v_mul_f32_e32 v184, v169, v187
	v_lshlrev_b32_e32 v197, 16, v191
	v_and_b32_e32 v191, 0xffff0000, v191
	v_rcp_f32_e32 v186, v186
	v_max_f32_e32 v169, 0x358637bd, v189
	v_rcp_f32_e32 v169, v169
	v_max_f32_e32 v195, 0x358637bd, v197
	v_max_f32_e32 v189, 0x358637bd, v191
	v_max_f32_e32 v185, 0x358637bd, v185
	v_max_f32_e32 v173, 0x358637bd, v173
	v_rcp_f32_e32 v195, v195
	v_cndmask_b32_e64 v196, v196, 1.0, s[20:21]
	v_cndmask_b32_e64 v188, v188, 1.0, s[20:21]
	v_rcp_f32_e32 v191, v189
	v_cndmask_b32_e64 v197, v186, 1.0, s[20:21]
	v_mul_f32_e32 v186, v185, v196
	v_mul_f32_e32 v185, v173, v188
	v_max_f32_e32 v173, 0x358637bd, v192
	v_cndmask_b32_e64 v169, v169, 1.0, s[20:21]
	v_mul_f32_e32 v189, v173, v169
	v_max_f32_e32 v193, 0x358637bd, v193
	v_cndmask_b32_e64 v195, v195, 1.0, s[20:21]
	v_max_f32_e32 v169, 0x358637bd, v194
	v_cndmask_b32_e64 v173, v191, 1.0, s[20:21]
	v_mul_f32_e32 v187, v198, v197
	v_mul_f32_e32 v188, v190, v199
	v_mul_f32_e32 v190, v193, v195
	v_mul_f32_e32 v191, v169, v173
	v_pk_mul_f32 v[126:127], v[126:127], v[188:189]
	v_pk_mul_f32 v[124:125], v[124:125], v[184:185]
	v_pk_mul_f32 v[122:123], v[122:123], v[190:191]
	v_pk_mul_f32 v[120:121], v[120:121], v[186:187]
	s_cbranch_scc1 .LBB0_826
	v_cvt_pk_bf16_f32 v184, v124, v125
	v_cvt_pk_bf16_f32 v185, v126, v127
	v_cvt_pk_bf16_f32 v186, v120, v121
	v_cvt_pk_bf16_f32 v187, v122, v123
	global_store_dwordx4 v[174:175], v[184:187], off
.LBB0_826:
	s_nop 1
	v_lshlrev_b32_e32 v186, 16, v144
	v_and_b32_e32 v187, 0xffff0000, v144
	v_lshlrev_b32_e32 v188, 16, v145
	v_and_b32_e32 v189, 0xffff0000, v145
	v_lshlrev_b32_e32 v144, 16, v146
	v_and_b32_e32 v145, 0xffff0000, v146
	v_max_f32_e32 v146, 0x358637bd, v186
	v_lshlrev_b32_e32 v169, 16, v148
	v_rcp_f32_e32 v146, v146
	v_max_f32_e32 v144, 0x358637bd, v144
	v_lshlrev_b32_e32 v190, 16, v147
	v_and_b32_e32 v186, 0xffff0000, v147
	v_max_f32_e32 v147, v169, v169
	v_rcp_f32_e32 v169, v144
	v_max_f32_e32 v147, 0x358637bd, v147
	v_cndmask_b32_e64 v146, v146, 1.0, s[20:21]
	v_mul_f32_e32 v144, v147, v146
	v_cndmask_b32_e64 v147, v169, 1.0, s[20:21]
	v_max_f32_e32 v169, 0x358637bd, v187
	v_rcp_f32_e32 v169, v169
	v_lshlrev_b32_e32 v184, 16, v150
	v_and_b32_e32 v148, 0xffff0000, v148
	v_max_f32_e32 v146, 0x358637bd, v184
	v_max_f32_e32 v145, 0x358637bd, v145
	v_mul_f32_e32 v146, v146, v147
	v_max_f32_e32 v147, v148, v148
	v_cndmask_b32_e64 v148, v169, 1.0, s[20:21]
	v_rcp_f32_e32 v169, v145
	v_and_b32_e32 v150, 0xffff0000, v150
	v_max_f32_e32 v147, 0x358637bd, v147
	v_mul_f32_e32 v145, v147, v148
	v_max_f32_e32 v147, v150, v150
	v_max_f32_e32 v150, 0x358637bd, v188
	v_lshlrev_b32_e32 v173, 16, v149
	v_max_f32_e32 v147, 0x358637bd, v147
	v_cndmask_b32_e64 v148, v169, 1.0, s[20:21]
	v_rcp_f32_e32 v150, v150
	v_mul_f32_e32 v147, v147, v148
	v_max_f32_e32 v148, v173, v173
	v_max_f32_e32 v169, 0x358637bd, v190
	v_rcp_f32_e32 v169, v169
	v_max_f32_e32 v173, 0x358637bd, v189
	v_rcp_f32_e32 v173, v173
	v_lshlrev_b32_e32 v185, 16, v151
	v_max_f32_e32 v148, 0x358637bd, v148
	v_cndmask_b32_e64 v150, v150, 1.0, s[20:21]
	v_mul_f32_e32 v148, v148, v150
	v_max_f32_e32 v150, 0x358637bd, v185
	v_cndmask_b32_e64 v169, v169, 1.0, s[20:21]
	v_mul_f32_e32 v150, v150, v169
	v_cndmask_b32_e64 v169, v173, 1.0, s[20:21]
	v_max_f32_e32 v173, 0x358637bd, v186
	v_rcp_f32_e32 v173, v173
	v_and_b32_e32 v149, 0xffff0000, v149
	v_and_b32_e32 v151, 0xffff0000, v151
	v_max_f32_e32 v149, 0x358637bd, v149
	v_mul_f32_e32 v149, v149, v169
	v_max_f32_e32 v151, 0x358637bd, v151
	v_cndmask_b32_e64 v169, v173, 1.0, s[20:21]
	v_mul_f32_e32 v151, v151, v169
	v_pk_mul_f32 v[92:93], v[92:93], v[144:145]
	v_cndmask_b32_e64 v144, 0, 1, s[20:21]
	v_pk_mul_f32 v[94:95], v[94:95], v[148:149]
	v_pk_mul_f32 v[90:91], v[90:91], v[150:151]
	v_cmp_ne_u32_e64 s[4:5], 1, v144
	s_andn2_b64 vcc, exec, s[20:21]
	v_pk_mul_f32 v[88:89], v[88:89], v[146:147]
	s_cbranch_vccnz .LBB0_828
	v_cvt_pk_bf16_f32 v144, v92, v93
	v_cvt_pk_bf16_f32 v145, v94, v95
	v_cvt_pk_bf16_f32 v146, v88, v89
	v_cvt_pk_bf16_f32 v147, v90, v91
	global_store_dwordx4 v[174:175], v[144:147], off offset:256
; __device__ __forceinline__ unsigned cvt_pk_bf16(float lo, float hi) { unsigned r; asm volatile("v_cvt_pk_bf16_f32 %0, %1, %2" : "=v"(r) : "v"(lo), "v"(hi)); return r; }
; __device__ __forceinline__ float bflo(unsigned w) { return __uint_as_float(w << 16); }
; __device__ __forceinline__ float bfhi(unsigned w) { return __uint_as_float(w & 0xffff0000u); }
;     __device__ __forceinline__ void operator()(f32x4 (&acc)[2][2][4][2], const Unit& u, int wr, int wc, int fr, int fq) const {
;     ...
; #pragma unroll
;                 for (int mm = 0; mm < 2; ++mm)
; #pragma unroll
;                     for (int bj = 0; bj < 2; ++bj) {
;                         const int m = 2 * m2 + mm;
;                         const u32x4 a4 = ga[mm][bj], b4 = gb[mm][bj];
;                         f32x4 g0 = (f32x4){bflo(a4.x), bfhi(a4.x), bflo(a4.y), bfhi(a4.y)}, g1 = (f32x4){bflo(a4.z), bfhi(a4.z), bflo(a4.w), bfhi(a4.w)};
;                         const f32x4 h0 = (f32x4){bflo(b4.x), bfhi(b4.x), bflo(b4.y), bfhi(b4.y)}, h1 = (f32x4){bflo(b4.z), bfhi(b4.z), bflo(b4.w), bfhi(b4.w)};
; #pragma unroll
;                         for (int j = 0; j < 4; ++j) {
;                             g0[j] = fmaxf(g0[j], 1e-6f) * (last ? 1.0f : __builtin_amdgcn_rcpf(fmaxf(h0[j], 1e-6f)));
;                             g1[j] = fmaxf(g1[j], 1e-6f) * (last ? 1.0f : __builtin_amdgcn_rcpf(fmaxf(h1[j], 1e-6f)));
;                         }
;                         acc[ai][bj][m][0] *= g0; acc[ai][bj][m][1] *= g1;
;                         if (last) {
;                             const f32x4 v0 = acc[ai][bj][m][0], v1 = acc[ai][bj][m][1];
;                             u32x4 w; w.x = cvt_pk_bf16(v0[0], v0[1]); w.y = cvt_pk_bf16(v0[2], v0[3]); w.z = cvt_pk_bf16(v1[0], v1[1]); w.w = cvt_pk_bf16(v1[2], v1[3]);
;                             *(u32x4*)(MB + (size_t)(row0 + ai * HALF + m * 16) * D + col0 + bj * HALF) = w;
;                         }
.LBB0_828:
	v_ashrrev_i32_e32 v173, 31, v172
	v_lshlrev_b32_e32 v150, 16, v136
	v_lshlrev_b64 v[144:145], 12, v[172:173]
	v_and_b32_e32 v151, 0xffff0000, v136
	v_lshlrev_b32_e32 v169, 16, v137
	v_and_b32_e32 v172, 0xffff0000, v137
	v_lshlrev_b32_e32 v136, 16, v138
	v_and_b32_e32 v137, 0xffff0000, v138
	v_max_f32_e32 v138, 0x358637bd, v150
	v_lshlrev_b32_e32 v146, 16, v140
	v_rcp_f32_e32 v138, v138
	v_max_f32_e32 v136, 0x358637bd, v136
	v_lshlrev_b32_e32 v173, 16, v139
	v_and_b32_e32 v150, 0xffff0000, v139
	v_max_f32_e32 v139, v146, v146
	v_rcp_f32_e32 v146, v136
	v_max_f32_e32 v139, 0x358637bd, v139
	v_cndmask_b32_e64 v138, v138, 1.0, s[20:21]
	v_mul_f32_e32 v136, v139, v138
	v_cndmask_b32_e64 v139, v146, 1.0, s[20:21]
	v_max_f32_e32 v146, 0x358637bd, v151
	v_rcp_f32_e32 v146, v146
	v_lshlrev_b32_e32 v148, 16, v142
	v_and_b32_e32 v140, 0xffff0000, v140
	v_max_f32_e32 v138, 0x358637bd, v148
	v_max_f32_e32 v137, 0x358637bd, v137
	v_mul_f32_e32 v138, v138, v139
	v_max_f32_e32 v139, v140, v140
	v_cndmask_b32_e64 v140, v146, 1.0, s[20:21]
	v_rcp_f32_e32 v146, v137
	v_and_b32_e32 v142, 0xffff0000, v142
	v_max_f32_e32 v139, 0x358637bd, v139
	v_mul_f32_e32 v137, v139, v140
	v_max_f32_e32 v139, v142, v142
	v_max_f32_e32 v142, 0x358637bd, v169
	v_lshlrev_b32_e32 v147, 16, v141
	v_max_f32_e32 v139, 0x358637bd, v139
	v_cndmask_b32_e64 v140, v146, 1.0, s[20:21]
	v_rcp_f32_e32 v142, v142
	v_mul_f32_e32 v139, v139, v140
	v_max_f32_e32 v140, v147, v147
	v_max_f32_e32 v146, 0x358637bd, v173
	v_rcp_f32_e32 v146, v146
	v_max_f32_e32 v147, 0x358637bd, v172
	v_rcp_f32_e32 v147, v147
	v_lshlrev_b32_e32 v149, 16, v143
	v_max_f32_e32 v140, 0x358637bd, v140
	v_cndmask_b32_e64 v142, v142, 1.0, s[20:21]
	v_mul_f32_e32 v140, v140, v142
	v_max_f32_e32 v142, 0x358637bd, v149
	v_cndmask_b32_e64 v146, v146, 1.0, s[20:21]
	v_mul_f32_e32 v142, v142, v146
	v_cndmask_b32_e64 v146, v147, 1.0, s[20:21]
	v_max_f32_e32 v147, 0x358637bd, v150
	v_rcp_f32_e32 v147, v147
	v_and_b32_e32 v141, 0xffff0000, v141
	v_and_b32_e32 v143, 0xffff0000, v143
	v_max_f32_e32 v141, 0x358637bd, v141
	v_mul_f32_e32 v141, v141, v146
	v_max_f32_e32 v143, 0x358637bd, v143
	v_cndmask_b32_e64 v146, v147, 1.0, s[20:21]
	v_mul_f32_e32 v143, v143, v146
	v_pk_mul_f32 v[116:117], v[116:117], v[136:137]
	v_lshl_add_u64 v[136:137], s[58:59], 0, v[144:145]
	v_pk_mul_f32 v[118:119], v[118:119], v[140:141]
	v_pk_mul_f32 v[114:115], v[114:115], v[142:143]
	v_pk_mul_f32 v[112:113], v[112:113], v[138:139]
	s_and_b64 vcc, exec, s[4:5]
	v_lshl_add_u64 v[136:137], v[166:167], 1, v[136:137]
	s_cbranch_vccnz .LBB0_830
	v_cvt_pk_bf16_f32 v138, v116, v117
	v_cvt_pk_bf16_f32 v139, v118, v119
	v_cvt_pk_bf16_f32 v140, v112, v113
	v_cvt_pk_bf16_f32 v141, v114, v115
	global_store_dwordx4 v[136:137], v[138:141], off
.LBB0_830:
	v_lshlrev_b32_e32 v142, 16, v128
	v_and_b32_e32 v143, 0xffff0000, v128
	v_lshlrev_b32_e32 v144, 16, v129
	v_and_b32_e32 v145, 0xffff0000, v129
	v_lshlrev_b32_e32 v128, 16, v130
	v_and_b32_e32 v129, 0xffff0000, v130
	v_max_f32_e32 v130, 0x358637bd, v142
	v_lshlrev_b32_e32 v138, 16, v132
	v_rcp_f32_e32 v130, v130
	v_max_f32_e32 v128, 0x358637bd, v128
	v_lshlrev_b32_e32 v146, 16, v131
	v_and_b32_e32 v142, 0xffff0000, v131
	v_max_f32_e32 v131, v138, v138
	v_rcp_f32_e32 v138, v128
	v_max_f32_e32 v131, 0x358637bd, v131
	v_cndmask_b32_e64 v130, v130, 1.0, s[20:21]
	v_mul_f32_e32 v128, v131, v130
	v_cndmask_b32_e64 v131, v138, 1.0, s[20:21]
	v_max_f32_e32 v138, 0x358637bd, v143
	v_rcp_f32_e32 v138, v138
	v_lshlrev_b32_e32 v140, 16, v134
	v_and_b32_e32 v132, 0xffff0000, v132
	v_max_f32_e32 v130, 0x358637bd, v140
	v_max_f32_e32 v129, 0x358637bd, v129
	v_mul_f32_e32 v130, v130, v131
	v_max_f32_e32 v131, v132, v132
	v_cndmask_b32_e64 v132, v138, 1.0, s[20:21]
	v_rcp_f32_e32 v138, v129
	v_and_b32_e32 v134, 0xffff0000, v134
	v_max_f32_e32 v131, 0x358637bd, v131
	v_mul_f32_e32 v129, v131, v132
	v_max_f32_e32 v131, v134, v134
	v_max_f32_e32 v134, 0x358637bd, v144
	v_lshlrev_b32_e32 v139, 16, v133
	v_max_f32_e32 v131, 0x358637bd, v131
	v_cndmask_b32_e64 v132, v138, 1.0, s[20:21]
	v_rcp_f32_e32 v134, v134
	v_mul_f32_e32 v131, v131, v132
	v_max_f32_e32 v132, v139, v139
	v_max_f32_e32 v138, 0x358637bd, v146
	v_rcp_f32_e32 v138, v138
	v_max_f32_e32 v139, 0x358637bd, v145
	v_rcp_f32_e32 v139, v139
	v_lshlrev_b32_e32 v141, 16, v135
	v_max_f32_e32 v132, 0x358637bd, v132
	v_cndmask_b32_e64 v134, v134, 1.0, s[20:21]
	v_mul_f32_e32 v132, v132, v134
	v_max_f32_e32 v134, 0x358637bd, v141
	v_cndmask_b32_e64 v138, v138, 1.0, s[20:21]
	v_mul_f32_e32 v134, v134, v138
	v_cndmask_b32_e64 v138, v139, 1.0, s[20:21]
	v_max_f32_e32 v139, 0x358637bd, v142
	v_rcp_f32_e32 v139, v139
	v_and_b32_e32 v133, 0xffff0000, v133
	v_and_b32_e32 v135, 0xffff0000, v135
	v_max_f32_e32 v133, 0x358637bd, v133
	v_mul_f32_e32 v133, v133, v138
	v_max_f32_e32 v135, 0x358637bd, v135
	v_cndmask_b32_e64 v138, v139, 1.0, s[20:21]
	v_mul_f32_e32 v135, v135, v138
	v_pk_mul_f32 v[86:87], v[86:87], v[132:133]
	v_pk_mul_f32 v[84:85], v[84:85], v[128:129]
	v_pk_mul_f32 v[82:83], v[82:83], v[134:135]
	s_and_b64 vcc, exec, s[4:5]
	v_pk_mul_f32 v[80:81], v[80:81], v[130:131]
	s_cbranch_vccnz .LBB0_832
	v_cvt_pk_bf16_f32 v128, v84, v85
	v_cvt_pk_bf16_f32 v129, v86, v87
	v_cvt_pk_bf16_f32 v130, v80, v81
	v_cvt_pk_bf16_f32 v131, v82, v83
	global_store_dwordx4 v[136:137], v[128:131], off offset:256
; __device__ __forceinline__ unsigned cvt_pk_bf16(float lo, float hi) { unsigned r; asm volatile("v_cvt_pk_bf16_f32 %0, %1, %2" : "=v"(r) : "v"(lo), "v"(hi)); return r; }
; __device__ __forceinline__ float bflo(unsigned w) { return __uint_as_float(w << 16); }
; __device__ __forceinline__ float bfhi(unsigned w) { return __uint_as_float(w & 0xffff0000u); }
;     __device__ __forceinline__ void operator()(f32x4 (&acc)[2][2][4][2], const Unit& u, int wr, int wc, int fr, int fq) const {
;     ...
;                         const bf16_t* zp = Z + (size_t)(row0 + ai * HALF + (2 * m2 + mm) * 16) * NZ + koff + col0 + bj * HALF;
;                         ga[mm][bj] = *(const u32x4*)zp;
;                         gb[mm][bj] = *(const u32x4*)(zp + noff);
;                     }
; #pragma unroll
;                 for (int mm = 0; mm < 2; ++mm)
; #pragma unroll
;                     for (int bj = 0; bj < 2; ++bj) {
;                         const int m = 2 * m2 + mm;
;                         const u32x4 a4 = ga[mm][bj], b4 = gb[mm][bj];
;                         f32x4 g0 = (f32x4){bflo(a4.x), bfhi(a4.x), bflo(a4.y), bfhi(a4.y)}, g1 = (f32x4){bflo(a4.z), bfhi(a4.z), bflo(a4.w), bfhi(a4.w)};
;                         const f32x4 h0 = (f32x4){bflo(b4.x), bfhi(b4.x), bflo(b4.y), bfhi(b4.y)}, h1 = (f32x4){bflo(b4.z), bfhi(b4.z), bflo(b4.w), bfhi(b4.w)};
; #pragma unroll
;                         for (int j = 0; j < 4; ++j) {
;                             g0[j] = fmaxf(g0[j], 1e-6f) * (last ? 1.0f : __builtin_amdgcn_rcpf(fmaxf(h0[j], 1e-6f)));
;                             g1[j] = fmaxf(g1[j], 1e-6f) * (last ? 1.0f : __builtin_amdgcn_rcpf(fmaxf(h1[j], 1e-6f)));
;                         }
;                         acc[ai][bj][m][0] *= g0; acc[ai][bj][m][1] *= g1;
;                         if (last) {
;                             const f32x4 v0 = acc[ai][bj][m][0], v1 = acc[ai][bj][m][1];
;                             u32x4 w; w.x = cvt_pk_bf16(v0[0], v0[1]); w.y = cvt_pk_bf16(v0[2], v0[3]); w.z = cvt_pk_bf16(v1[0], v1[1]); w.w = cvt_pk_bf16(v1[2], v1[3]);
;                             *(u32x4*)(MB + (size_t)(row0 + ai * HALF + m * 16) * D + col0 + bj * HALF) = w;
;                         }
.LBB0_832:
	s_nop 1
	v_or_b32_e32 v128, 32, v168
	v_mov_b64_e32 v[130:131], s[22:23]
	v_mad_i64_i32 v[132:133], s[24:25], v128, s46, v[130:131]
	v_lshl_add_u64 v[132:133], v[132:133], 0, v[170:171]
	v_add_co_u32_e32 v134, vcc, 0x2000, v132
	v_or_b32_e32 v172, 48, v168
	s_nop 0
	v_addc_co_u32_e32 v135, vcc, 0, v133, vcc
	v_lshl_add_u64 v[132:133], v[132:133], 0, s[12:13]
	global_load_dwordx4 v[184:187], v[134:135], off offset:2048
	v_lshl_add_u64 v[134:135], v[132:133], 0, s[0:1]
	global_load_dwordx4 v[188:191], v[134:135], off
	v_mad_i64_i32 v[130:131], s[24:25], v172, s46, v[130:131]
	v_lshl_add_u64 v[130:131], v[130:131], 0, v[170:171]
	v_ashrrev_i32_e32 v129, 31, v128
	v_lshl_add_u64 v[192:193], v[130:131], 0, s[12:13]
	v_add_co_u32_e32 v140, vcc, s37, v130
	v_lshlrev_b64 v[174:175], 12, v[128:129]
	v_lshl_add_u64 v[128:129], v[192:193], 0, s[0:1]
	v_addc_co_u32_e32 v141, vcc, 0, v131, vcc
	global_load_dwordx4 v[148:151], v[132:133], off offset:256
	global_load_dwordx4 v[144:147], v[134:135], off offset:256
	global_load_dwordx4 v[136:139], v[128:129], off
	s_nop 0
	global_load_dwordx4 v[128:131], v[128:129], off offset:256
	s_nop 0
	global_load_dwordx4 v[140:143], v[140:141], off offset:2048
	s_nop 0
	global_load_dwordx4 v[132:135], v[192:193], off offset:256
	v_lshl_add_u64 v[174:175], s[58:59], 0, v[174:175]
	s_and_b64 vcc, exec, s[4:5]
	v_lshl_add_u64 v[174:175], v[166:167], 1, v[174:175]
	s_waitcnt vmcnt(7)
	v_lshlrev_b32_e32 v193, 16, v187
	v_and_b32_e32 v194, 0xffff0000, v187
	s_waitcnt vmcnt(6)
	v_lshlrev_b32_e32 v187, 16, v188
	v_and_b32_e32 v188, 0xffff0000, v188
	v_lshlrev_b32_e32 v196, 16, v190
	v_lshlrev_b32_e32 v169, 16, v184
	v_and_b32_e32 v173, 0xffff0000, v184
	v_lshlrev_b32_e32 v184, 16, v185
	v_and_b32_e32 v192, 0xffff0000, v185
	v_lshlrev_b32_e32 v185, 16, v186
	v_and_b32_e32 v186, 0xffff0000, v186
	v_lshlrev_b32_e32 v195, 16, v189
	v_and_b32_e32 v189, 0xffff0000, v189
	v_and_b32_e32 v190, 0xffff0000, v190
	v_max_f32_e32 v196, 0x358637bd, v196
	v_max_f32_e32 v188, 0x358637bd, v188
	v_max_f32_e32 v198, 0x358637bd, v186
	v_max_f32_e32 v186, 0x358637bd, v190
	v_max_f32_e32 v189, 0x358637bd, v189
	v_rcp_f32_e32 v196, v196
	v_rcp_f32_e32 v188, v188
	v_rcp_f32_e32 v186, v186
	v_rcp_f32_e32 v189, v189
	v_max_f32_e32 v187, 0x358637bd, v187
	v_lshlrev_b32_e32 v197, 16, v191
	v_max_f32_e32 v190, 0x358637bd, v184
	v_max_f32_e32 v184, 0x358637bd, v195
	v_rcp_f32_e32 v187, v187
	v_and_b32_e32 v191, 0xffff0000, v191
	v_max_f32_e32 v185, 0x358637bd, v185
	v_max_f32_e32 v173, 0x358637bd, v173
	v_rcp_f32_e32 v184, v184
	v_cndmask_b32_e64 v196, v196, 1.0, s[20:21]
	v_cndmask_b32_e64 v188, v188, 1.0, s[20:21]
	v_max_f32_e32 v195, 0x358637bd, v197
	v_cndmask_b32_e64 v197, v186, 1.0, s[20:21]
	v_mul_f32_e32 v186, v185, v196
	v_mul_f32_e32 v185, v173, v188
	v_cndmask_b32_e64 v173, v189, 1.0, s[20:21]
	v_max_f32_e32 v189, 0x358637bd, v191
	v_max_f32_e32 v169, 0x358637bd, v169
	v_rcp_f32_e32 v195, v195
	v_cndmask_b32_e64 v187, v187, 1.0, s[20:21]
	v_rcp_f32_e32 v191, v189
	v_cndmask_b32_e64 v199, v184, 1.0, s[20:21]
	v_mul_f32_e32 v184, v169, v187
	v_max_f32_e32 v169, 0x358637bd, v192
	v_mul_f32_e32 v189, v169, v173
	v_max_f32_e32 v193, 0x358637bd, v193
	v_cndmask_b32_e64 v195, v195, 1.0, s[20:21]
	v_max_f32_e32 v169, 0x358637bd, v194
	v_cndmask_b32_e64 v173, v191, 1.0, s[20:21]
	v_mul_f32_e32 v187, v198, v197
	v_mul_f32_e32 v188, v190, v199
	v_mul_f32_e32 v190, v193, v195
	v_mul_f32_e32 v191, v169, v173
	v_pk_mul_f32 v[110:111], v[110:111], v[188:189]
	v_pk_mul_f32 v[108:109], v[108:109], v[184:185]
	v_pk_mul_f32 v[106:107], v[106:107], v[190:191]
	v_pk_mul_f32 v[104:105], v[104:105], v[186:187]
	s_cbranch_vccnz .LBB0_834
	v_cvt_pk_bf16_f32 v184, v108, v109
	v_cvt_pk_bf16_f32 v185, v110, v111
	v_cvt_pk_bf16_f32 v186, v104, v105
	v_cvt_pk_bf16_f32 v187, v106, v107
	global_store_dwordx4 v[174:175], v[184:187], off
.LBB0_834:
	s_waitcnt vmcnt(4)
	s_nop 0
	v_lshlrev_b32_e32 v186, 16, v144
	v_and_b32_e32 v187, 0xffff0000, v144
	v_lshlrev_b32_e32 v188, 16, v145
	v_and_b32_e32 v189, 0xffff0000, v145
	v_lshlrev_b32_e32 v144, 16, v146
	v_and_b32_e32 v145, 0xffff0000, v146
	v_max_f32_e32 v146, 0x358637bd, v186
	v_lshlrev_b32_e32 v169, 16, v148
	v_rcp_f32_e32 v146, v146
	v_max_f32_e32 v144, 0x358637bd, v144
	v_lshlrev_b32_e32 v190, 16, v147
	v_and_b32_e32 v186, 0xffff0000, v147
	v_max_f32_e32 v147, v169, v169
	v_rcp_f32_e32 v169, v144
	v_max_f32_e32 v147, 0x358637bd, v147
	v_cndmask_b32_e64 v146, v146, 1.0, s[20:21]
	v_mul_f32_e32 v144, v147, v146
	v_cndmask_b32_e64 v147, v169, 1.0, s[20:21]
	v_max_f32_e32 v169, 0x358637bd, v187
	v_rcp_f32_e32 v169, v169
	v_lshlrev_b32_e32 v184, 16, v150
	v_and_b32_e32 v148, 0xffff0000, v148
	v_max_f32_e32 v146, 0x358637bd, v184
	v_max_f32_e32 v145, 0x358637bd, v145
	v_mul_f32_e32 v146, v146, v147
	v_max_f32_e32 v147, v148, v148
	v_cndmask_b32_e64 v148, v169, 1.0, s[20:21]
	v_rcp_f32_e32 v169, v145
	v_and_b32_e32 v150, 0xffff0000, v150
	v_max_f32_e32 v147, 0x358637bd, v147
	v_mul_f32_e32 v145, v147, v148
	v_max_f32_e32 v147, v150, v150
	v_max_f32_e32 v150, 0x358637bd, v188
	v_lshlrev_b32_e32 v173, 16, v149
	v_max_f32_e32 v147, 0x358637bd, v147
	v_cndmask_b32_e64 v148, v169, 1.0, s[20:21]
	v_rcp_f32_e32 v150, v150
	v_mul_f32_e32 v147, v147, v148
	v_max_f32_e32 v148, v173, v173
	v_max_f32_e32 v169, 0x358637bd, v190
	v_rcp_f32_e32 v169, v169
	v_max_f32_e32 v173, 0x358637bd, v189
	v_rcp_f32_e32 v173, v173
	v_lshlrev_b32_e32 v185, 16, v151
	v_max_f32_e32 v148, 0x358637bd, v148
	v_cndmask_b32_e64 v150, v150, 1.0, s[20:21]
	v_mul_f32_e32 v148, v148, v150
	v_max_f32_e32 v150, 0x358637bd, v185
	v_cndmask_b32_e64 v169, v169, 1.0, s[20:21]
	v_mul_f32_e32 v150, v150, v169
	v_cndmask_b32_e64 v169, v173, 1.0, s[20:21]
	v_max_f32_e32 v173, 0x358637bd, v186
	v_rcp_f32_e32 v173, v173
	v_and_b32_e32 v149, 0xffff0000, v149
	v_and_b32_e32 v151, 0xffff0000, v151
	v_max_f32_e32 v149, 0x358637bd, v149
	v_mul_f32_e32 v149, v149, v169
	v_max_f32_e32 v151, 0x358637bd, v151
	v_cndmask_b32_e64 v169, v173, 1.0, s[20:21]
	v_mul_f32_e32 v151, v151, v169
	v_pk_mul_f32 v[78:79], v[78:79], v[148:149]
	v_pk_mul_f32 v[76:77], v[76:77], v[144:145]
	v_pk_mul_f32 v[74:75], v[74:75], v[150:151]
	s_and_b64 vcc, exec, s[4:5]
	v_pk_mul_f32 v[72:73], v[72:73], v[146:147]
	s_cbranch_vccnz .LBB0_836
	v_cvt_pk_bf16_f32 v144, v76, v77
	v_cvt_pk_bf16_f32 v145, v78, v79
	v_cvt_pk_bf16_f32 v146, v72, v73
	v_cvt_pk_bf16_f32 v147, v74, v75
	global_store_dwordx4 v[174:175], v[144:147], off offset:256
; __device__ __forceinline__ unsigned cvt_pk_bf16(float lo, float hi) { unsigned r; asm volatile("v_cvt_pk_bf16_f32 %0, %1, %2" : "=v"(r) : "v"(lo), "v"(hi)); return r; }
; __device__ __forceinline__ float bflo(unsigned w) { return __uint_as_float(w << 16); }
; __device__ __forceinline__ float bfhi(unsigned w) { return __uint_as_float(w & 0xffff0000u); }
;     __device__ __forceinline__ void operator()(f32x4 (&acc)[2][2][4][2], const Unit& u, int wr, int wc, int fr, int fq) const {
;     ...
; #pragma unroll
;                 for (int mm = 0; mm < 2; ++mm)
; #pragma unroll
;                     for (int bj = 0; bj < 2; ++bj) {
;                         const int m = 2 * m2 + mm;
;                         const u32x4 a4 = ga[mm][bj], b4 = gb[mm][bj];
;                         f32x4 g0 = (f32x4){bflo(a4.x), bfhi(a4.x), bflo(a4.y), bfhi(a4.y)}, g1 = (f32x4){bflo(a4.z), bfhi(a4.z), bflo(a4.w), bfhi(a4.w)};
;                         const f32x4 h0 = (f32x4){bflo(b4.x), bfhi(b4.x), bflo(b4.y), bfhi(b4.y)}, h1 = (f32x4){bflo(b4.z), bfhi(b4.z), bflo(b4.w), bfhi(b4.w)};
; #pragma unroll
;                         for (int j = 0; j < 4; ++j) {
;                             g0[j] = fmaxf(g0[j], 1e-6f) * (last ? 1.0f : __builtin_amdgcn_rcpf(fmaxf(h0[j], 1e-6f)));
;                             g1[j] = fmaxf(g1[j], 1e-6f) * (last ? 1.0f : __builtin_amdgcn_rcpf(fmaxf(h1[j], 1e-6f)));
;                         }
;                         acc[ai][bj][m][0] *= g0; acc[ai][bj][m][1] *= g1;
;                         if (last) {
;                             const f32x4 v0 = acc[ai][bj][m][0], v1 = acc[ai][bj][m][1];
;                             u32x4 w; w.x = cvt_pk_bf16(v0[0], v0[1]); w.y = cvt_pk_bf16(v0[2], v0[3]); w.z = cvt_pk_bf16(v1[0], v1[1]); w.w = cvt_pk_bf16(v1[2], v1[3]);
;                             *(u32x4*)(MB + (size_t)(row0 + ai * HALF + m * 16) * D + col0 + bj * HALF) = w;
;                         }
.LBB0_836:
	v_ashrrev_i32_e32 v173, 31, v172
	s_waitcnt vmcnt(3)
	v_lshlrev_b32_e32 v150, 16, v136
	v_lshlrev_b64 v[144:145], 12, v[172:173]
	v_and_b32_e32 v151, 0xffff0000, v136
	v_lshlrev_b32_e32 v169, 16, v137
	v_and_b32_e32 v172, 0xffff0000, v137
	v_lshlrev_b32_e32 v136, 16, v138
	v_and_b32_e32 v137, 0xffff0000, v138
	v_max_f32_e32 v138, 0x358637bd, v150
	s_waitcnt vmcnt(1)
	v_lshlrev_b32_e32 v146, 16, v140
	v_rcp_f32_e32 v138, v138
	v_max_f32_e32 v136, 0x358637bd, v136
	v_lshlrev_b32_e32 v173, 16, v139
	v_and_b32_e32 v150, 0xffff0000, v139
	v_max_f32_e32 v139, v146, v146
	v_rcp_f32_e32 v146, v136
	v_max_f32_e32 v139, 0x358637bd, v139
	v_cndmask_b32_e64 v138, v138, 1.0, s[20:21]
	v_mul_f32_e32 v136, v139, v138
	v_cndmask_b32_e64 v139, v146, 1.0, s[20:21]
	v_max_f32_e32 v146, 0x358637bd, v151
	v_rcp_f32_e32 v146, v146
	v_lshlrev_b32_e32 v148, 16, v142
	v_and_b32_e32 v140, 0xffff0000, v140
	v_max_f32_e32 v138, 0x358637bd, v148
	v_max_f32_e32 v137, 0x358637bd, v137
	v_mul_f32_e32 v138, v138, v139
	v_max_f32_e32 v139, v140, v140
	v_cndmask_b32_e64 v140, v146, 1.0, s[20:21]
	v_rcp_f32_e32 v146, v137
	v_and_b32_e32 v142, 0xffff0000, v142
	v_max_f32_e32 v139, 0x358637bd, v139
	v_mul_f32_e32 v137, v139, v140
	v_max_f32_e32 v139, v142, v142
	v_max_f32_e32 v142, 0x358637bd, v169
	v_lshlrev_b32_e32 v147, 16, v141
	v_max_f32_e32 v139, 0x358637bd, v139
	v_cndmask_b32_e64 v140, v146, 1.0, s[20:21]
	v_rcp_f32_e32 v142, v142
	v_mul_f32_e32 v139, v139, v140
	v_max_f32_e32 v140, v147, v147
	v_max_f32_e32 v146, 0x358637bd, v173
	v_rcp_f32_e32 v146, v146
	v_max_f32_e32 v147, 0x358637bd, v172
	v_rcp_f32_e32 v147, v147
	v_lshlrev_b32_e32 v149, 16, v143
	v_max_f32_e32 v140, 0x358637bd, v140
	v_cndmask_b32_e64 v142, v142, 1.0, s[20:21]
	v_mul_f32_e32 v140, v140, v142
	v_max_f32_e32 v142, 0x358637bd, v149
	v_cndmask_b32_e64 v146, v146, 1.0, s[20:21]
	v_mul_f32_e32 v142, v142, v146
	v_cndmask_b32_e64 v146, v147, 1.0, s[20:21]
	v_max_f32_e32 v147, 0x358637bd, v150
	v_rcp_f32_e32 v147, v147
	v_and_b32_e32 v141, 0xffff0000, v141
	v_and_b32_e32 v143, 0xffff0000, v143
	v_max_f32_e32 v141, 0x358637bd, v141
	v_mul_f32_e32 v141, v141, v146
	v_max_f32_e32 v143, 0x358637bd, v143
	v_cndmask_b32_e64 v146, v147, 1.0, s[20:21]
	v_mul_f32_e32 v143, v143, v146
	v_pk_mul_f32 v[100:101], v[100:101], v[136:137]
	v_lshl_add_u64 v[136:137], s[58:59], 0, v[144:145]
	v_pk_mul_f32 v[102:103], v[102:103], v[140:141]
	v_pk_mul_f32 v[98:99], v[98:99], v[142:143]
	v_pk_mul_f32 v[96:97], v[96:97], v[138:139]
	s_and_b64 vcc, exec, s[4:5]
	v_lshl_add_u64 v[136:137], v[166:167], 1, v[136:137]
	s_cbranch_vccnz .LBB0_838
	v_cvt_pk_bf16_f32 v138, v100, v101
	v_cvt_pk_bf16_f32 v139, v102, v103
	v_cvt_pk_bf16_f32 v140, v96, v97
	v_cvt_pk_bf16_f32 v141, v98, v99
	global_store_dwordx4 v[136:137], v[138:141], off
.LBB0_838:
	v_lshlrev_b32_e32 v142, 16, v128
	v_and_b32_e32 v143, 0xffff0000, v128
	v_lshlrev_b32_e32 v144, 16, v129
	v_and_b32_e32 v145, 0xffff0000, v129
	v_lshlrev_b32_e32 v128, 16, v130
	v_and_b32_e32 v129, 0xffff0000, v130
	v_max_f32_e32 v130, 0x358637bd, v142
	s_waitcnt vmcnt(0)
	v_lshlrev_b32_e32 v138, 16, v132
	v_rcp_f32_e32 v130, v130
	v_max_f32_e32 v128, 0x358637bd, v128
	v_lshlrev_b32_e32 v146, 16, v131
	v_and_b32_e32 v142, 0xffff0000, v131
	v_max_f32_e32 v131, v138, v138
	v_rcp_f32_e32 v138, v128
	v_max_f32_e32 v131, 0x358637bd, v131
	v_cndmask_b32_e64 v130, v130, 1.0, s[20:21]
	v_mul_f32_e32 v128, v131, v130
	v_cndmask_b32_e64 v131, v138, 1.0, s[20:21]
	v_max_f32_e32 v138, 0x358637bd, v143
	v_rcp_f32_e32 v138, v138
	v_lshlrev_b32_e32 v140, 16, v134
	v_and_b32_e32 v132, 0xffff0000, v132
	v_max_f32_e32 v130, 0x358637bd, v140
	v_max_f32_e32 v129, 0x358637bd, v129
	v_mul_f32_e32 v130, v130, v131
	v_max_f32_e32 v131, v132, v132
	v_cndmask_b32_e64 v132, v138, 1.0, s[20:21]
	v_rcp_f32_e32 v138, v129
	v_and_b32_e32 v134, 0xffff0000, v134
	v_max_f32_e32 v131, 0x358637bd, v131
	v_mul_f32_e32 v129, v131, v132
	v_max_f32_e32 v131, v134, v134
	v_max_f32_e32 v134, 0x358637bd, v144
	v_lshlrev_b32_e32 v139, 16, v133
	v_max_f32_e32 v131, 0x358637bd, v131
	v_cndmask_b32_e64 v132, v138, 1.0, s[20:21]
	v_rcp_f32_e32 v134, v134
	v_mul_f32_e32 v131, v131, v132
	v_max_f32_e32 v132, v139, v139
	v_max_f32_e32 v138, 0x358637bd, v146
	v_rcp_f32_e32 v138, v138
	v_max_f32_e32 v139, 0x358637bd, v145
	v_rcp_f32_e32 v139, v139
	v_lshlrev_b32_e32 v141, 16, v135
	v_max_f32_e32 v132, 0x358637bd, v132
	v_cndmask_b32_e64 v134, v134, 1.0, s[20:21]
	v_mul_f32_e32 v132, v132, v134
	v_max_f32_e32 v134, 0x358637bd, v141
	v_cndmask_b32_e64 v138, v138, 1.0, s[20:21]
	v_mul_f32_e32 v134, v134, v138
	v_cndmask_b32_e64 v138, v139, 1.0, s[20:21]
	v_max_f32_e32 v139, 0x358637bd, v142
	v_rcp_f32_e32 v139, v139
	v_and_b32_e32 v133, 0xffff0000, v133
	v_and_b32_e32 v135, 0xffff0000, v135
	v_max_f32_e32 v133, 0x358637bd, v133
	v_mul_f32_e32 v133, v133, v138
	v_max_f32_e32 v135, 0x358637bd, v135
	v_cndmask_b32_e64 v138, v139, 1.0, s[20:21]
	v_mul_f32_e32 v135, v135, v138
	v_pk_mul_f32 v[70:71], v[70:71], v[132:133]
	v_pk_mul_f32 v[68:69], v[68:69], v[128:129]
	v_pk_mul_f32 v[66:67], v[66:67], v[134:135]
	s_and_b64 vcc, exec, s[4:5]
	v_pk_mul_f32 v[64:65], v[64:65], v[130:131]
	s_cbranch_vccnz .LBB0_840
	v_cvt_pk_bf16_f32 v128, v68, v69
	v_cvt_pk_bf16_f32 v129, v70, v71
	v_cvt_pk_bf16_f32 v130, v64, v65
	v_cvt_pk_bf16_f32 v131, v66, v67
	global_store_dwordx4 v[136:137], v[128:131], off offset:256
; __device__ __forceinline__ unsigned cvt_pk_bf16(float lo, float hi) { unsigned r; asm volatile("v_cvt_pk_bf16_f32 %0, %1, %2" : "=v"(r) : "v"(lo), "v"(hi)); return r; }
; __device__ __forceinline__ float bflo(unsigned w) { return __uint_as_float(w << 16); }
; __device__ __forceinline__ float bfhi(unsigned w) { return __uint_as_float(w & 0xffff0000u); }
;     __device__ __forceinline__ void operator()(f32x4 (&acc)[2][2][4][2], const Unit& u, int wr, int wc, int fr, int fq) const {
;     ...
;                         const bf16_t* zp = Z + (size_t)(row0 + ai * HALF + (2 * m2 + mm) * 16) * NZ + koff + col0 + bj * HALF;
;                         ga[mm][bj] = *(const u32x4*)zp;
;                         gb[mm][bj] = *(const u32x4*)(zp + noff);
;                     }
; #pragma unroll
;                 for (int mm = 0; mm < 2; ++mm)
; #pragma unroll
;                     for (int bj = 0; bj < 2; ++bj) {
;                         const int m = 2 * m2 + mm;
;                         const u32x4 a4 = ga[mm][bj], b4 = gb[mm][bj];
;                         f32x4 g0 = (f32x4){bflo(a4.x), bfhi(a4.x), bflo(a4.y), bfhi(a4.y)}, g1 = (f32x4){bflo(a4.z), bfhi(a4.z), bflo(a4.w), bfhi(a4.w)};
;                         const f32x4 h0 = (f32x4){bflo(b4.x), bfhi(b4.x), bflo(b4.y), bfhi(b4.y)}, h1 = (f32x4){bflo(b4.z), bfhi(b4.z), bflo(b4.w), bfhi(b4.w)};
; #pragma unroll
;                         for (int j = 0; j < 4; ++j) {
;                             g0[j] = fmaxf(g0[j], 1e-6f) * (last ? 1.0f : __builtin_amdgcn_rcpf(fmaxf(h0[j], 1e-6f)));
;                             g1[j] = fmaxf(g1[j], 1e-6f) * (last ? 1.0f : __builtin_amdgcn_rcpf(fmaxf(h1[j], 1e-6f)));
;                         }
;                         acc[ai][bj][m][0] *= g0; acc[ai][bj][m][1] *= g1;
;                         if (last) {
;                             const f32x4 v0 = acc[ai][bj][m][0], v1 = acc[ai][bj][m][1];
;                             u32x4 w; w.x = cvt_pk_bf16(v0[0], v0[1]); w.y = cvt_pk_bf16(v0[2], v0[3]); w.z = cvt_pk_bf16(v1[0], v1[1]); w.w = cvt_pk_bf16(v1[2], v1[3]);
;                             *(u32x4*)(MB + (size_t)(row0 + ai * HALF + m * 16) * D + col0 + bj * HALF) = w;
;                         }
.LBB0_840:
	s_nop 1
	v_add_u32_e32 v128, 0x80, v168
	v_mov_b64_e32 v[130:131], s[22:23]
	v_mad_i64_i32 v[132:133], s[24:25], v128, s46, v[130:131]
	v_lshl_add_u64 v[132:133], v[132:133], 0, v[170:171]
	v_add_co_u32_e32 v134, vcc, 0x2000, v132
	v_add_u32_e32 v172, 0x90, v168
	s_nop 0
	v_addc_co_u32_e32 v135, vcc, 0, v133, vcc
	v_lshl_add_u64 v[132:133], v[132:133], 0, s[12:13]
	global_load_dwordx4 v[184:187], v[134:135], off offset:2048
	v_lshl_add_u64 v[134:135], v[132:133], 0, s[0:1]
	global_load_dwordx4 v[188:191], v[134:135], off
	v_mad_i64_i32 v[130:131], s[24:25], v172, s46, v[130:131]
	v_lshl_add_u64 v[130:131], v[130:131], 0, v[170:171]
	v_ashrrev_i32_e32 v129, 31, v128
	v_lshl_add_u64 v[192:193], v[130:131], 0, s[12:13]
	v_add_co_u32_e32 v140, vcc, s37, v130
	v_lshlrev_b64 v[174:175], 12, v[128:129]
	v_lshl_add_u64 v[128:129], v[192:193], 0, s[0:1]
	v_addc_co_u32_e32 v141, vcc, 0, v131, vcc
	global_load_dwordx4 v[148:151], v[132:133], off offset:256
	global_load_dwordx4 v[144:147], v[134:135], off offset:256
	global_load_dwordx4 v[136:139], v[128:129], off
	s_nop 0
	global_load_dwordx4 v[128:131], v[128:129], off offset:256
	s_nop 0
	global_load_dwordx4 v[140:143], v[140:141], off offset:2048
	s_nop 0
	global_load_dwordx4 v[132:135], v[192:193], off offset:256
	v_lshl_add_u64 v[174:175], s[58:59], 0, v[174:175]
	s_and_b64 vcc, exec, s[4:5]
	v_lshl_add_u64 v[174:175], v[166:167], 1, v[174:175]
	s_waitcnt vmcnt(7)
	v_lshlrev_b32_e32 v193, 16, v187
	v_and_b32_e32 v194, 0xffff0000, v187
	s_waitcnt vmcnt(6)
	v_lshlrev_b32_e32 v187, 16, v188
	v_and_b32_e32 v188, 0xffff0000, v188
	v_lshlrev_b32_e32 v196, 16, v190
	v_lshlrev_b32_e32 v169, 16, v184
	v_and_b32_e32 v173, 0xffff0000, v184
	v_lshlrev_b32_e32 v184, 16, v185
	v_and_b32_e32 v192, 0xffff0000, v185
	v_lshlrev_b32_e32 v185, 16, v186
	v_and_b32_e32 v186, 0xffff0000, v186
	v_lshlrev_b32_e32 v195, 16, v189
	v_and_b32_e32 v189, 0xffff0000, v189
	v_and_b32_e32 v190, 0xffff0000, v190
	v_max_f32_e32 v196, 0x358637bd, v196
	v_max_f32_e32 v188, 0x358637bd, v188
	v_max_f32_e32 v198, 0x358637bd, v186
	v_max_f32_e32 v186, 0x358637bd, v190
	v_max_f32_e32 v189, 0x358637bd, v189
	v_rcp_f32_e32 v196, v196
	v_rcp_f32_e32 v188, v188
	v_rcp_f32_e32 v186, v186
	v_rcp_f32_e32 v189, v189
	v_max_f32_e32 v187, 0x358637bd, v187
	v_lshlrev_b32_e32 v197, 16, v191
	v_max_f32_e32 v190, 0x358637bd, v184
	v_max_f32_e32 v184, 0x358637bd, v195
	v_rcp_f32_e32 v187, v187
	v_and_b32_e32 v191, 0xffff0000, v191
	v_max_f32_e32 v185, 0x358637bd, v185
	v_max_f32_e32 v173, 0x358637bd, v173
	v_rcp_f32_e32 v184, v184
	v_cndmask_b32_e64 v196, v196, 1.0, s[20:21]
	v_cndmask_b32_e64 v188, v188, 1.0, s[20:21]
	v_max_f32_e32 v195, 0x358637bd, v197
	v_cndmask_b32_e64 v197, v186, 1.0, s[20:21]
	v_mul_f32_e32 v186, v185, v196
	v_mul_f32_e32 v185, v173, v188
	v_cndmask_b32_e64 v173, v189, 1.0, s[20:21]
	v_max_f32_e32 v189, 0x358637bd, v191
	v_max_f32_e32 v169, 0x358637bd, v169
	v_rcp_f32_e32 v195, v195
	v_cndmask_b32_e64 v187, v187, 1.0, s[20:21]
	v_rcp_f32_e32 v191, v189
	v_cndmask_b32_e64 v199, v184, 1.0, s[20:21]
	v_mul_f32_e32 v184, v169, v187
	v_max_f32_e32 v169, 0x358637bd, v192
	v_mul_f32_e32 v189, v169, v173
	v_max_f32_e32 v193, 0x358637bd, v193
	v_cndmask_b32_e64 v195, v195, 1.0, s[20:21]
	v_max_f32_e32 v169, 0x358637bd, v194
	v_cndmask_b32_e64 v173, v191, 1.0, s[20:21]
	v_mul_f32_e32 v187, v198, v197
	v_mul_f32_e32 v188, v190, v199
	v_mul_f32_e32 v190, v193, v195
	v_mul_f32_e32 v191, v169, v173
	v_pk_mul_f32 v[62:63], v[62:63], v[188:189]
	v_pk_mul_f32 v[60:61], v[60:61], v[184:185]
	v_pk_mul_f32 v[58:59], v[58:59], v[190:191]
	v_pk_mul_f32 v[56:57], v[56:57], v[186:187]
	s_cbranch_vccnz .LBB0_842
	v_cvt_pk_bf16_f32 v184, v60, v61
	v_cvt_pk_bf16_f32 v185, v62, v63
	v_cvt_pk_bf16_f32 v186, v56, v57
	v_cvt_pk_bf16_f32 v187, v58, v59
	global_store_dwordx4 v[174:175], v[184:187], off
.LBB0_842:
	s_waitcnt vmcnt(4)
	s_nop 0
	v_lshlrev_b32_e32 v186, 16, v144
	v_and_b32_e32 v187, 0xffff0000, v144
	v_lshlrev_b32_e32 v188, 16, v145
	v_and_b32_e32 v189, 0xffff0000, v145
	v_lshlrev_b32_e32 v144, 16, v146
	v_and_b32_e32 v145, 0xffff0000, v146
	v_max_f32_e32 v146, 0x358637bd, v186
	v_lshlrev_b32_e32 v169, 16, v148
	v_rcp_f32_e32 v146, v146
	v_max_f32_e32 v144, 0x358637bd, v144
	v_lshlrev_b32_e32 v190, 16, v147
	v_and_b32_e32 v186, 0xffff0000, v147
	v_max_f32_e32 v147, v169, v169
	v_rcp_f32_e32 v169, v144
	v_max_f32_e32 v147, 0x358637bd, v147
	v_cndmask_b32_e64 v146, v146, 1.0, s[20:21]
	v_mul_f32_e32 v144, v147, v146
	v_cndmask_b32_e64 v147, v169, 1.0, s[20:21]
	v_max_f32_e32 v169, 0x358637bd, v187
	v_rcp_f32_e32 v169, v169
	v_lshlrev_b32_e32 v184, 16, v150
	v_and_b32_e32 v148, 0xffff0000, v148
	v_max_f32_e32 v146, 0x358637bd, v184
	v_max_f32_e32 v145, 0x358637bd, v145
	v_mul_f32_e32 v146, v146, v147
	v_max_f32_e32 v147, v148, v148
	v_cndmask_b32_e64 v148, v169, 1.0, s[20:21]
	v_rcp_f32_e32 v169, v145
	v_and_b32_e32 v150, 0xffff0000, v150
	v_max_f32_e32 v147, 0x358637bd, v147
	v_mul_f32_e32 v145, v147, v148
	v_max_f32_e32 v147, v150, v150
	v_max_f32_e32 v150, 0x358637bd, v188
	v_lshlrev_b32_e32 v173, 16, v149
	v_max_f32_e32 v147, 0x358637bd, v147
	v_cndmask_b32_e64 v148, v169, 1.0, s[20:21]
	v_rcp_f32_e32 v150, v150
	v_mul_f32_e32 v147, v147, v148
	v_max_f32_e32 v148, v173, v173
	v_max_f32_e32 v169, 0x358637bd, v190
	v_rcp_f32_e32 v169, v169
	v_max_f32_e32 v173, 0x358637bd, v189
	v_rcp_f32_e32 v173, v173
	v_lshlrev_b32_e32 v185, 16, v151
	v_max_f32_e32 v148, 0x358637bd, v148
	v_cndmask_b32_e64 v150, v150, 1.0, s[20:21]
	v_mul_f32_e32 v148, v148, v150
	v_max_f32_e32 v150, 0x358637bd, v185
	v_cndmask_b32_e64 v169, v169, 1.0, s[20:21]
	v_mul_f32_e32 v150, v150, v169
	v_cndmask_b32_e64 v169, v173, 1.0, s[20:21]
	v_max_f32_e32 v173, 0x358637bd, v186
	v_rcp_f32_e32 v173, v173
	v_and_b32_e32 v149, 0xffff0000, v149
	v_and_b32_e32 v151, 0xffff0000, v151
	v_max_f32_e32 v149, 0x358637bd, v149
	v_mul_f32_e32 v149, v149, v169
	v_max_f32_e32 v151, 0x358637bd, v151
	v_cndmask_b32_e64 v169, v173, 1.0, s[20:21]
	v_mul_f32_e32 v151, v151, v169
	v_pk_mul_f32 v[30:31], v[30:31], v[148:149]
	v_pk_mul_f32 v[28:29], v[28:29], v[144:145]
	v_pk_mul_f32 v[26:27], v[26:27], v[150:151]
	s_and_b64 vcc, exec, s[4:5]
	v_pk_mul_f32 v[24:25], v[24:25], v[146:147]
	s_cbranch_vccnz .LBB0_844
	v_cvt_pk_bf16_f32 v144, v28, v29
	v_cvt_pk_bf16_f32 v145, v30, v31
	v_cvt_pk_bf16_f32 v146, v24, v25
	v_cvt_pk_bf16_f32 v147, v26, v27
	global_store_dwordx4 v[174:175], v[144:147], off offset:256
; __device__ __forceinline__ unsigned cvt_pk_bf16(float lo, float hi) { unsigned r; asm volatile("v_cvt_pk_bf16_f32 %0, %1, %2" : "=v"(r) : "v"(lo), "v"(hi)); return r; }
; __device__ __forceinline__ float bflo(unsigned w) { return __uint_as_float(w << 16); }
; __device__ __forceinline__ float bfhi(unsigned w) { return __uint_as_float(w & 0xffff0000u); }
;     __device__ __forceinline__ void operator()(f32x4 (&acc)[2][2][4][2], const Unit& u, int wr, int wc, int fr, int fq) const {
;     ...
; #pragma unroll
;                 for (int mm = 0; mm < 2; ++mm)
; #pragma unroll
;                     for (int bj = 0; bj < 2; ++bj) {
;                         const int m = 2 * m2 + mm;
;                         const u32x4 a4 = ga[mm][bj], b4 = gb[mm][bj];
;                         f32x4 g0 = (f32x4){bflo(a4.x), bfhi(a4.x), bflo(a4.y), bfhi(a4.y)}, g1 = (f32x4){bflo(a4.z), bfhi(a4.z), bflo(a4.w), bfhi(a4.w)};
;                         const f32x4 h0 = (f32x4){bflo(b4.x), bfhi(b4.x), bflo(b4.y), bfhi(b4.y)}, h1 = (f32x4){bflo(b4.z), bfhi(b4.z), bflo(b4.w), bfhi(b4.w)};
; #pragma unroll
;                         for (int j = 0; j < 4; ++j) {
;                             g0[j] = fmaxf(g0[j], 1e-6f) * (last ? 1.0f : __builtin_amdgcn_rcpf(fmaxf(h0[j], 1e-6f)));
;                             g1[j] = fmaxf(g1[j], 1e-6f) * (last ? 1.0f : __builtin_amdgcn_rcpf(fmaxf(h1[j], 1e-6f)));
;                         }
;                         acc[ai][bj][m][0] *= g0; acc[ai][bj][m][1] *= g1;
;                         if (last) {
;                             const f32x4 v0 = acc[ai][bj][m][0], v1 = acc[ai][bj][m][1];
;                             u32x4 w; w.x = cvt_pk_bf16(v0[0], v0[1]); w.y = cvt_pk_bf16(v0[2], v0[3]); w.z = cvt_pk_bf16(v1[0], v1[1]); w.w = cvt_pk_bf16(v1[2], v1[3]);
;                             *(u32x4*)(MB + (size_t)(row0 + ai * HALF + m * 16) * D + col0 + bj * HALF) = w;
;                         }
.LBB0_844:
	v_ashrrev_i32_e32 v173, 31, v172
	s_waitcnt vmcnt(3)
	v_lshlrev_b32_e32 v150, 16, v136
	v_lshlrev_b64 v[144:145], 12, v[172:173]
	v_and_b32_e32 v151, 0xffff0000, v136
	v_lshlrev_b32_e32 v169, 16, v137
	v_and_b32_e32 v172, 0xffff0000, v137
	v_lshlrev_b32_e32 v136, 16, v138
	v_and_b32_e32 v137, 0xffff0000, v138
	v_max_f32_e32 v138, 0x358637bd, v150
	s_waitcnt vmcnt(1)
	v_lshlrev_b32_e32 v146, 16, v140
	v_rcp_f32_e32 v138, v138
	v_max_f32_e32 v136, 0x358637bd, v136
	v_lshlrev_b32_e32 v173, 16, v139
	v_and_b32_e32 v150, 0xffff0000, v139
	v_max_f32_e32 v139, v146, v146
	v_rcp_f32_e32 v146, v136
	v_max_f32_e32 v139, 0x358637bd, v139
	v_cndmask_b32_e64 v138, v138, 1.0, s[20:21]
	v_mul_f32_e32 v136, v139, v138
	v_cndmask_b32_e64 v139, v146, 1.0, s[20:21]
	v_max_f32_e32 v146, 0x358637bd, v151
	v_rcp_f32_e32 v146, v146
	v_lshlrev_b32_e32 v148, 16, v142
	v_and_b32_e32 v140, 0xffff0000, v140
	v_max_f32_e32 v138, 0x358637bd, v148
	v_max_f32_e32 v137, 0x358637bd, v137
	v_mul_f32_e32 v138, v138, v139
	v_max_f32_e32 v139, v140, v140
	v_cndmask_b32_e64 v140, v146, 1.0, s[20:21]
	v_rcp_f32_e32 v146, v137
	v_and_b32_e32 v142, 0xffff0000, v142
	v_max_f32_e32 v139, 0x358637bd, v139
	v_mul_f32_e32 v137, v139, v140
	v_max_f32_e32 v139, v142, v142
	v_max_f32_e32 v142, 0x358637bd, v169
	v_lshlrev_b32_e32 v147, 16, v141
	v_max_f32_e32 v139, 0x358637bd, v139
	v_cndmask_b32_e64 v140, v146, 1.0, s[20:21]
	v_rcp_f32_e32 v142, v142
	v_mul_f32_e32 v139, v139, v140
	v_max_f32_e32 v140, v147, v147
	v_max_f32_e32 v146, 0x358637bd, v173
	v_rcp_f32_e32 v146, v146
	v_max_f32_e32 v147, 0x358637bd, v172
	v_rcp_f32_e32 v147, v147
	v_lshlrev_b32_e32 v149, 16, v143
	v_max_f32_e32 v140, 0x358637bd, v140
	v_cndmask_b32_e64 v142, v142, 1.0, s[20:21]
	v_mul_f32_e32 v140, v140, v142
	v_max_f32_e32 v142, 0x358637bd, v149
	v_cndmask_b32_e64 v146, v146, 1.0, s[20:21]
	v_mul_f32_e32 v142, v142, v146
	v_cndmask_b32_e64 v146, v147, 1.0, s[20:21]
	v_max_f32_e32 v147, 0x358637bd, v150
	v_rcp_f32_e32 v147, v147
	v_and_b32_e32 v141, 0xffff0000, v141
	v_and_b32_e32 v143, 0xffff0000, v143
	v_max_f32_e32 v141, 0x358637bd, v141
	v_mul_f32_e32 v141, v141, v146
	v_max_f32_e32 v143, 0x358637bd, v143
	v_cndmask_b32_e64 v146, v147, 1.0, s[20:21]
	v_mul_f32_e32 v143, v143, v146
	v_pk_mul_f32 v[52:53], v[52:53], v[136:137]
	v_lshl_add_u64 v[136:137], s[58:59], 0, v[144:145]
	v_pk_mul_f32 v[54:55], v[54:55], v[140:141]
	v_pk_mul_f32 v[50:51], v[50:51], v[142:143]
	v_pk_mul_f32 v[48:49], v[48:49], v[138:139]
	s_and_b64 vcc, exec, s[4:5]
	v_lshl_add_u64 v[136:137], v[166:167], 1, v[136:137]
	s_cbranch_vccnz .LBB0_846
	v_cvt_pk_bf16_f32 v138, v52, v53
	v_cvt_pk_bf16_f32 v139, v54, v55
	v_cvt_pk_bf16_f32 v140, v48, v49
	v_cvt_pk_bf16_f32 v141, v50, v51
	global_store_dwordx4 v[136:137], v[138:141], off
.LBB0_846:
	v_lshlrev_b32_e32 v142, 16, v128
	v_and_b32_e32 v143, 0xffff0000, v128
	v_lshlrev_b32_e32 v144, 16, v129
	v_and_b32_e32 v145, 0xffff0000, v129
	v_lshlrev_b32_e32 v128, 16, v130
	v_and_b32_e32 v129, 0xffff0000, v130
	v_max_f32_e32 v130, 0x358637bd, v142
	s_waitcnt vmcnt(0)
	v_lshlrev_b32_e32 v138, 16, v132
	v_rcp_f32_e32 v130, v130
	v_max_f32_e32 v128, 0x358637bd, v128
	v_lshlrev_b32_e32 v146, 16, v131
	v_and_b32_e32 v142, 0xffff0000, v131
	v_max_f32_e32 v131, v138, v138
	v_rcp_f32_e32 v138, v128
	v_max_f32_e32 v131, 0x358637bd, v131
	v_cndmask_b32_e64 v130, v130, 1.0, s[20:21]
	v_mul_f32_e32 v128, v131, v130
	v_cndmask_b32_e64 v131, v138, 1.0, s[20:21]
	v_max_f32_e32 v138, 0x358637bd, v143
	v_rcp_f32_e32 v138, v138
	v_lshlrev_b32_e32 v140, 16, v134
	v_and_b32_e32 v132, 0xffff0000, v132
	v_max_f32_e32 v130, 0x358637bd, v140
	v_max_f32_e32 v129, 0x358637bd, v129
	v_mul_f32_e32 v130, v130, v131
	v_max_f32_e32 v131, v132, v132
	v_cndmask_b32_e64 v132, v138, 1.0, s[20:21]
	v_rcp_f32_e32 v138, v129
	v_and_b32_e32 v134, 0xffff0000, v134
	v_max_f32_e32 v131, 0x358637bd, v131
	v_mul_f32_e32 v129, v131, v132
	v_max_f32_e32 v131, v134, v134
	v_max_f32_e32 v134, 0x358637bd, v144
	v_lshlrev_b32_e32 v139, 16, v133
	v_max_f32_e32 v131, 0x358637bd, v131
	v_cndmask_b32_e64 v132, v138, 1.0, s[20:21]
	v_rcp_f32_e32 v134, v134
	v_mul_f32_e32 v131, v131, v132
	v_max_f32_e32 v132, v139, v139
	v_max_f32_e32 v138, 0x358637bd, v146
	v_rcp_f32_e32 v138, v138
	v_max_f32_e32 v139, 0x358637bd, v145
	v_rcp_f32_e32 v139, v139
	v_lshlrev_b32_e32 v141, 16, v135
	v_max_f32_e32 v132, 0x358637bd, v132
	v_cndmask_b32_e64 v134, v134, 1.0, s[20:21]
	v_mul_f32_e32 v132, v132, v134
	v_max_f32_e32 v134, 0x358637bd, v141
	v_cndmask_b32_e64 v138, v138, 1.0, s[20:21]
	v_mul_f32_e32 v134, v134, v138
	v_cndmask_b32_e64 v138, v139, 1.0, s[20:21]
	v_max_f32_e32 v139, 0x358637bd, v142
	v_rcp_f32_e32 v139, v139
	v_and_b32_e32 v133, 0xffff0000, v133
	v_and_b32_e32 v135, 0xffff0000, v135
	v_max_f32_e32 v133, 0x358637bd, v133
	v_mul_f32_e32 v133, v133, v138
	v_max_f32_e32 v135, 0x358637bd, v135
	v_cndmask_b32_e64 v138, v139, 1.0, s[20:21]
	v_mul_f32_e32 v135, v135, v138
	v_pk_mul_f32 v[22:23], v[22:23], v[132:133]
	v_pk_mul_f32 v[20:21], v[20:21], v[128:129]
	v_pk_mul_f32 v[18:19], v[18:19], v[134:135]
	s_and_b64 vcc, exec, s[4:5]
	v_pk_mul_f32 v[16:17], v[16:17], v[130:131]
	s_cbranch_vccnz .LBB0_848
	v_cvt_pk_bf16_f32 v128, v20, v21
	v_cvt_pk_bf16_f32 v129, v22, v23
	v_cvt_pk_bf16_f32 v130, v16, v17
	v_cvt_pk_bf16_f32 v131, v18, v19
	global_store_dwordx4 v[136:137], v[128:131], off offset:256
; __device__ __forceinline__ unsigned cvt_pk_bf16(float lo, float hi) { unsigned r; asm volatile("v_cvt_pk_bf16_f32 %0, %1, %2" : "=v"(r) : "v"(lo), "v"(hi)); return r; }
; __device__ __forceinline__ float bflo(unsigned w) { return __uint_as_float(w << 16); }
; __device__ __forceinline__ float bfhi(unsigned w) { return __uint_as_float(w & 0xffff0000u); }
;     __device__ __forceinline__ void operator()(f32x4 (&acc)[2][2][4][2], const Unit& u, int wr, int wc, int fr, int fq) const {
;     ...
;                         const bf16_t* zp = Z + (size_t)(row0 + ai * HALF + (2 * m2 + mm) * 16) * NZ + koff + col0 + bj * HALF;
;                         ga[mm][bj] = *(const u32x4*)zp;
;                         gb[mm][bj] = *(const u32x4*)(zp + noff);
;                     }
; #pragma unroll
;                 for (int mm = 0; mm < 2; ++mm)
; #pragma unroll
;                     for (int bj = 0; bj < 2; ++bj) {
;                         const int m = 2 * m2 + mm;
;                         const u32x4 a4 = ga[mm][bj], b4 = gb[mm][bj];
;                         f32x4 g0 = (f32x4){bflo(a4.x), bfhi(a4.x), bflo(a4.y), bfhi(a4.y)}, g1 = (f32x4){bflo(a4.z), bfhi(a4.z), bflo(a4.w), bfhi(a4.w)};
;                         const f32x4 h0 = (f32x4){bflo(b4.x), bfhi(b4.x), bflo(b4.y), bfhi(b4.y)}, h1 = (f32x4){bflo(b4.z), bfhi(b4.z), bflo(b4.w), bfhi(b4.w)};
; #pragma unroll
;                         for (int j = 0; j < 4; ++j) {
;                             g0[j] = fmaxf(g0[j], 1e-6f) * (last ? 1.0f : __builtin_amdgcn_rcpf(fmaxf(h0[j], 1e-6f)));
;                             g1[j] = fmaxf(g1[j], 1e-6f) * (last ? 1.0f : __builtin_amdgcn_rcpf(fmaxf(h1[j], 1e-6f)));
;                         }
;                         acc[ai][bj][m][0] *= g0; acc[ai][bj][m][1] *= g1;
;                         if (last) {
;                             const f32x4 v0 = acc[ai][bj][m][0], v1 = acc[ai][bj][m][1];
;                             u32x4 w; w.x = cvt_pk_bf16(v0[0], v0[1]); w.y = cvt_pk_bf16(v0[2], v0[3]); w.z = cvt_pk_bf16(v1[0], v1[1]); w.w = cvt_pk_bf16(v1[2], v1[3]);
;                             *(u32x4*)(MB + (size_t)(row0 + ai * HALF + m * 16) * D + col0 + bj * HALF) = w;
;                         }
.LBB0_848:
	s_nop 1
	v_add_u32_e32 v128, 0xa0, v168
	v_mov_b64_e32 v[130:131], s[22:23]
	v_mad_i64_i32 v[132:133], s[22:23], v128, s46, v[130:131]
	v_lshl_add_u64 v[132:133], v[132:133], 0, v[170:171]
	v_add_co_u32_e32 v134, vcc, 0x2000, v132
	v_add_u32_e32 v168, 0xb0, v168
	s_nop 0
	v_addc_co_u32_e32 v135, vcc, 0, v133, vcc
	v_lshl_add_u64 v[132:133], v[132:133], 0, s[12:13]
	global_load_dwordx4 v[172:175], v[134:135], off offset:2048
	v_lshl_add_u64 v[134:135], v[132:133], 0, s[0:1]
	global_load_dwordx4 v[184:187], v[134:135], off
	v_mad_i64_i32 v[130:131], s[22:23], v168, s46, v[130:131]
	v_lshl_add_u64 v[130:131], v[130:131], 0, v[170:171]
	v_ashrrev_i32_e32 v129, 31, v128
	v_lshl_add_u64 v[188:189], v[130:131], 0, s[12:13]
	v_add_co_u32_e32 v140, vcc, s37, v130
	v_lshlrev_b64 v[170:171], 12, v[128:129]
	v_lshl_add_u64 v[128:129], v[188:189], 0, s[0:1]
	v_addc_co_u32_e32 v141, vcc, 0, v131, vcc
	global_load_dwordx4 v[148:151], v[132:133], off offset:256
	global_load_dwordx4 v[144:147], v[134:135], off offset:256
	global_load_dwordx4 v[136:139], v[128:129], off
	s_nop 0
	global_load_dwordx4 v[128:131], v[128:129], off offset:256
	s_nop 0
	global_load_dwordx4 v[140:143], v[140:141], off offset:2048
	s_nop 0
	global_load_dwordx4 v[132:135], v[188:189], off offset:256
	v_lshl_add_u64 v[170:171], s[58:59], 0, v[170:171]
	s_and_b64 vcc, exec, s[4:5]
	v_lshl_add_u64 v[170:171], v[166:167], 1, v[170:171]
	s_waitcnt vmcnt(7)
	v_lshlrev_b32_e32 v190, 16, v175
	v_and_b32_e32 v191, 0xffff0000, v175
	s_waitcnt vmcnt(6)
	v_lshlrev_b32_e32 v175, 16, v184
	v_lshlrev_b32_e32 v169, 16, v172
	v_and_b32_e32 v172, 0xffff0000, v172
	v_and_b32_e32 v184, 0xffff0000, v184
	v_lshlrev_b32_e32 v192, 16, v185
	v_and_b32_e32 v185, 0xffff0000, v185
	v_max_f32_e32 v175, 0x358637bd, v175
	v_max_f32_e32 v195, 0x358637bd, v172
	v_max_f32_e32 v172, 0x358637bd, v184
	v_rcp_f32_e32 v175, v175
	v_lshlrev_b32_e32 v188, 16, v173
	v_and_b32_e32 v189, 0xffff0000, v173
	v_lshlrev_b32_e32 v173, 16, v174
	v_and_b32_e32 v174, 0xffff0000, v174
	v_lshlrev_b32_e32 v193, 16, v186
	v_and_b32_e32 v186, 0xffff0000, v186
	v_lshlrev_b32_e32 v194, 16, v187
	v_and_b32_e32 v187, 0xffff0000, v187
	v_max_f32_e32 v185, 0x358637bd, v185
	v_rcp_f32_e32 v172, v172
	v_rcp_f32_e32 v185, v185
	v_max_f32_e32 v193, 0x358637bd, v193
	v_max_f32_e32 v184, 0x358637bd, v174
	v_max_f32_e32 v174, 0x358637bd, v186
	v_max_f32_e32 v186, 0x358637bd, v188
	v_max_f32_e32 v188, 0x358637bd, v192
	v_max_f32_e32 v192, 0x358637bd, v194
	v_max_f32_e32 v187, 0x358637bd, v187
	v_max_f32_e32 v169, 0x358637bd, v169
	v_rcp_f32_e32 v193, v193
	v_rcp_f32_e32 v174, v174
	v_rcp_f32_e32 v188, v188
	v_rcp_f32_e32 v192, v192
	v_cndmask_b32_e64 v175, v175, 1.0, s[20:21]
	v_rcp_f32_e32 v187, v187
	v_cndmask_b32_e64 v194, v172, 1.0, s[20:21]
	v_mul_f32_e32 v172, v169, v175
	v_max_f32_e32 v169, 0x358637bd, v189
	v_cndmask_b32_e64 v185, v185, 1.0, s[20:21]
	v_mul_f32_e32 v185, v169, v185
	v_max_f32_e32 v173, 0x358637bd, v173
	v_max_f32_e32 v190, 0x358637bd, v190
	v_cndmask_b32_e64 v193, v193, 1.0, s[20:21]
	v_cndmask_b32_e64 v196, v174, 1.0, s[20:21]
	v_cndmask_b32_e64 v188, v188, 1.0, s[20:21]
	v_cndmask_b32_e64 v192, v192, 1.0, s[20:21]
	v_max_f32_e32 v169, 0x358637bd, v191
	v_cndmask_b32_e64 v187, v187, 1.0, s[20:21]
	v_mul_f32_e32 v174, v173, v193
	v_mul_f32_e32 v173, v195, v194
	v_mul_f32_e32 v175, v184, v196
	v_mul_f32_e32 v184, v186, v188
	v_mul_f32_e32 v186, v190, v192
	v_mul_f32_e32 v187, v169, v187
	v_pk_mul_f32 v[46:47], v[46:47], v[184:185]
	v_pk_mul_f32 v[44:45], v[44:45], v[172:173]
	v_pk_mul_f32 v[42:43], v[42:43], v[186:187]
	v_pk_mul_f32 v[40:41], v[40:41], v[174:175]
	s_cbranch_vccnz .LBB0_850
	v_cvt_pk_bf16_f32 v172, v44, v45
	v_cvt_pk_bf16_f32 v173, v46, v47
	v_cvt_pk_bf16_f32 v174, v40, v41
	v_cvt_pk_bf16_f32 v175, v42, v43
	global_store_dwordx4 v[170:171], v[172:175], off
.LBB0_850:
	s_waitcnt vmcnt(4)
	s_nop 0
	v_lshlrev_b32_e32 v175, 16, v144
	v_and_b32_e32 v184, 0xffff0000, v144
	v_lshlrev_b32_e32 v185, 16, v145
	v_and_b32_e32 v186, 0xffff0000, v145
	v_lshlrev_b32_e32 v144, 16, v146
	v_and_b32_e32 v145, 0xffff0000, v146
	v_max_f32_e32 v146, 0x358637bd, v175
	v_lshlrev_b32_e32 v169, 16, v148
	v_rcp_f32_e32 v146, v146
	v_max_f32_e32 v144, 0x358637bd, v144
	v_lshlrev_b32_e32 v187, 16, v147
	v_and_b32_e32 v175, 0xffff0000, v147
	v_max_f32_e32 v147, v169, v169
	v_rcp_f32_e32 v169, v144
	v_max_f32_e32 v147, 0x358637bd, v147
	v_cndmask_b32_e64 v146, v146, 1.0, s[20:21]
	v_mul_f32_e32 v144, v147, v146
	v_cndmask_b32_e64 v147, v169, 1.0, s[20:21]
	v_max_f32_e32 v169, 0x358637bd, v184
	v_rcp_f32_e32 v169, v169
	v_lshlrev_b32_e32 v173, 16, v150
	v_and_b32_e32 v148, 0xffff0000, v148
	v_max_f32_e32 v146, 0x358637bd, v173
	v_max_f32_e32 v145, 0x358637bd, v145
	v_mul_f32_e32 v146, v146, v147
	v_max_f32_e32 v147, v148, v148
	v_cndmask_b32_e64 v148, v169, 1.0, s[20:21]
	v_rcp_f32_e32 v169, v145
	v_and_b32_e32 v150, 0xffff0000, v150
	v_max_f32_e32 v147, 0x358637bd, v147
	v_mul_f32_e32 v145, v147, v148
	v_max_f32_e32 v147, v150, v150
	v_max_f32_e32 v150, 0x358637bd, v185
	v_lshlrev_b32_e32 v172, 16, v149
	v_max_f32_e32 v147, 0x358637bd, v147
	v_cndmask_b32_e64 v148, v169, 1.0, s[20:21]
	v_rcp_f32_e32 v150, v150
	v_mul_f32_e32 v147, v147, v148
	v_max_f32_e32 v148, v172, v172
	v_max_f32_e32 v169, 0x358637bd, v187
	v_rcp_f32_e32 v169, v169
	v_max_f32_e32 v172, 0x358637bd, v186
	v_rcp_f32_e32 v172, v172
	v_lshlrev_b32_e32 v174, 16, v151
	v_max_f32_e32 v148, 0x358637bd, v148
	v_cndmask_b32_e64 v150, v150, 1.0, s[20:21]
	v_mul_f32_e32 v148, v148, v150
	v_max_f32_e32 v150, 0x358637bd, v174
	v_cndmask_b32_e64 v169, v169, 1.0, s[20:21]
	v_mul_f32_e32 v150, v150, v169
	v_cndmask_b32_e64 v169, v172, 1.0, s[20:21]
	v_max_f32_e32 v172, 0x358637bd, v175
	v_rcp_f32_e32 v172, v172
	v_and_b32_e32 v149, 0xffff0000, v149
	v_and_b32_e32 v151, 0xffff0000, v151
	v_max_f32_e32 v149, 0x358637bd, v149
	v_mul_f32_e32 v149, v149, v169
	v_max_f32_e32 v151, 0x358637bd, v151
	v_cndmask_b32_e64 v169, v172, 1.0, s[20:21]
	v_mul_f32_e32 v151, v151, v169
	v_pk_mul_f32 v[14:15], v[14:15], v[148:149]
	v_pk_mul_f32 v[12:13], v[12:13], v[144:145]
	v_pk_mul_f32 v[10:11], v[10:11], v[150:151]
	s_and_b64 vcc, exec, s[4:5]
	v_pk_mul_f32 v[8:9], v[8:9], v[146:147]
	s_cbranch_vccnz .LBB0_852
	v_cvt_pk_bf16_f32 v144, v12, v13
	v_cvt_pk_bf16_f32 v145, v14, v15
	v_cvt_pk_bf16_f32 v146, v8, v9
	v_cvt_pk_bf16_f32 v147, v10, v11
	global_store_dwordx4 v[170:171], v[144:147], off offset:256
; __device__ __forceinline__ unsigned cvt_pk_bf16(float lo, float hi) { unsigned r; asm volatile("v_cvt_pk_bf16_f32 %0, %1, %2" : "=v"(r) : "v"(lo), "v"(hi)); return r; }
; __device__ __forceinline__ float bflo(unsigned w) { return __uint_as_float(w << 16); }
; __device__ __forceinline__ float bfhi(unsigned w) { return __uint_as_float(w & 0xffff0000u); }
;     __device__ __forceinline__ void operator()(f32x4 (&acc)[2][2][4][2], const Unit& u, int wr, int wc, int fr, int fq) const {
;     ...
;                         const bf16_t* zp = Z + (size_t)(row0 + ai * HALF + (2 * m2 + mm) * 16) * NZ + koff + col0 + bj * HALF;
;                         ga[mm][bj] = *(const u32x4*)zp;
;                         gb[mm][bj] = *(const u32x4*)(zp + noff);
;                     }
; #pragma unroll
;                 for (int mm = 0; mm < 2; ++mm)
; #pragma unroll
;                     for (int bj = 0; bj < 2; ++bj) {
;                         const int m = 2 * m2 + mm;
;                         const u32x4 a4 = ga[mm][bj], b4 = gb[mm][bj];
;                         f32x4 g0 = (f32x4){bflo(a4.x), bfhi(a4.x), bflo(a4.y), bfhi(a4.y)}, g1 = (f32x4){bflo(a4.z), bfhi(a4.z), bflo(a4.w), bfhi(a4.w)};
;                         const f32x4 h0 = (f32x4){bflo(b4.x), bfhi(b4.x), bflo(b4.y), bfhi(b4.y)}, h1 = (f32x4){bflo(b4.z), bfhi(b4.z), bflo(b4.w), bfhi(b4.w)};
; #pragma unroll
;                         for (int j = 0; j < 4; ++j) {
;                             g0[j] = fmaxf(g0[j], 1e-6f) * (last ? 1.0f : __builtin_amdgcn_rcpf(fmaxf(h0[j], 1e-6f)));
;                             g1[j] = fmaxf(g1[j], 1e-6f) * (last ? 1.0f : __builtin_amdgcn_rcpf(fmaxf(h1[j], 1e-6f)));
;                         }
;                         acc[ai][bj][m][0] *= g0; acc[ai][bj][m][1] *= g1;
;                         if (last) {
;                             const f32x4 v0 = acc[ai][bj][m][0], v1 = acc[ai][bj][m][1];
;                             u32x4 w; w.x = cvt_pk_bf16(v0[0], v0[1]); w.y = cvt_pk_bf16(v0[2], v0[3]); w.z = cvt_pk_bf16(v1[0], v1[1]); w.w = cvt_pk_bf16(v1[2], v1[3]);
;                             *(u32x4*)(MB + (size_t)(row0 + ai * HALF + m * 16) * D + col0 + bj * HALF) = w;
;                         }
.LBB0_852:
	v_ashrrev_i32_e32 v169, 31, v168
	s_waitcnt vmcnt(3)
	v_lshlrev_b32_e32 v150, 16, v136
	v_lshlrev_b64 v[144:145], 12, v[168:169]
	v_and_b32_e32 v151, 0xffff0000, v136
	v_lshlrev_b32_e32 v168, 16, v137
	v_and_b32_e32 v169, 0xffff0000, v137
	v_lshlrev_b32_e32 v136, 16, v138
	v_and_b32_e32 v137, 0xffff0000, v138
	v_max_f32_e32 v138, 0x358637bd, v150
	s_waitcnt vmcnt(1)
	v_lshlrev_b32_e32 v146, 16, v140
	v_rcp_f32_e32 v138, v138
	v_max_f32_e32 v136, 0x358637bd, v136
	v_lshlrev_b32_e32 v170, 16, v139
	v_and_b32_e32 v150, 0xffff0000, v139
	v_max_f32_e32 v139, v146, v146
	v_rcp_f32_e32 v146, v136
	v_max_f32_e32 v139, 0x358637bd, v139
	v_cndmask_b32_e64 v138, v138, 1.0, s[20:21]
	v_mul_f32_e32 v136, v139, v138
	v_cndmask_b32_e64 v139, v146, 1.0, s[20:21]
	v_max_f32_e32 v146, 0x358637bd, v151
	v_rcp_f32_e32 v146, v146
	v_lshlrev_b32_e32 v148, 16, v142
	v_and_b32_e32 v140, 0xffff0000, v140
	v_max_f32_e32 v138, 0x358637bd, v148
	v_max_f32_e32 v137, 0x358637bd, v137
	v_mul_f32_e32 v138, v138, v139
	v_max_f32_e32 v139, v140, v140
	v_cndmask_b32_e64 v140, v146, 1.0, s[20:21]
	v_rcp_f32_e32 v146, v137
	v_and_b32_e32 v142, 0xffff0000, v142
	v_max_f32_e32 v139, 0x358637bd, v139
	v_mul_f32_e32 v137, v139, v140
	v_max_f32_e32 v139, v142, v142
	v_max_f32_e32 v142, 0x358637bd, v168
	v_lshlrev_b32_e32 v147, 16, v141
	v_max_f32_e32 v139, 0x358637bd, v139
	v_cndmask_b32_e64 v140, v146, 1.0, s[20:21]
	v_rcp_f32_e32 v142, v142
	v_mul_f32_e32 v139, v139, v140
	v_max_f32_e32 v140, v147, v147
	v_max_f32_e32 v146, 0x358637bd, v170
	v_rcp_f32_e32 v146, v146
	v_max_f32_e32 v147, 0x358637bd, v169
	v_rcp_f32_e32 v147, v147
	v_lshlrev_b32_e32 v149, 16, v143
	v_max_f32_e32 v140, 0x358637bd, v140
	v_cndmask_b32_e64 v142, v142, 1.0, s[20:21]
	v_mul_f32_e32 v140, v140, v142
	v_max_f32_e32 v142, 0x358637bd, v149
	v_cndmask_b32_e64 v146, v146, 1.0, s[20:21]
	v_mul_f32_e32 v142, v142, v146
	v_cndmask_b32_e64 v146, v147, 1.0, s[20:21]
	v_max_f32_e32 v147, 0x358637bd, v150
	v_rcp_f32_e32 v147, v147
	v_and_b32_e32 v141, 0xffff0000, v141
	v_and_b32_e32 v143, 0xffff0000, v143
	v_max_f32_e32 v141, 0x358637bd, v141
	v_mul_f32_e32 v141, v141, v146
	v_max_f32_e32 v143, 0x358637bd, v143
	v_cndmask_b32_e64 v146, v147, 1.0, s[20:21]
	v_mul_f32_e32 v143, v143, v146
	v_pk_mul_f32 v[36:37], v[36:37], v[136:137]
	v_lshl_add_u64 v[136:137], s[58:59], 0, v[144:145]
	v_pk_mul_f32 v[38:39], v[38:39], v[140:141]
	v_pk_mul_f32 v[34:35], v[34:35], v[142:143]
	v_pk_mul_f32 v[32:33], v[32:33], v[138:139]
	s_and_b64 vcc, exec, s[4:5]
	v_lshl_add_u64 v[136:137], v[166:167], 1, v[136:137]
	s_cbranch_vccnz .LBB0_854
	v_cvt_pk_bf16_f32 v138, v36, v37
	v_cvt_pk_bf16_f32 v139, v38, v39
	v_cvt_pk_bf16_f32 v140, v32, v33
	v_cvt_pk_bf16_f32 v141, v34, v35
	global_store_dwordx4 v[136:137], v[138:141], off
.LBB0_854:
	v_lshlrev_b32_e32 v142, 16, v128
	v_and_b32_e32 v143, 0xffff0000, v128
	v_lshlrev_b32_e32 v144, 16, v129
	v_and_b32_e32 v145, 0xffff0000, v129
	v_lshlrev_b32_e32 v128, 16, v130
	v_and_b32_e32 v129, 0xffff0000, v130
	v_max_f32_e32 v130, 0x358637bd, v142
	s_waitcnt vmcnt(0)
	v_lshlrev_b32_e32 v138, 16, v132
	v_rcp_f32_e32 v130, v130
	v_max_f32_e32 v128, 0x358637bd, v128
	v_lshlrev_b32_e32 v146, 16, v131
	v_and_b32_e32 v142, 0xffff0000, v131
	v_max_f32_e32 v131, v138, v138
	v_rcp_f32_e32 v138, v128
	v_max_f32_e32 v131, 0x358637bd, v131
	v_cndmask_b32_e64 v130, v130, 1.0, s[20:21]
	v_mul_f32_e32 v128, v131, v130
	v_cndmask_b32_e64 v131, v138, 1.0, s[20:21]
	v_max_f32_e32 v138, 0x358637bd, v143
	v_rcp_f32_e32 v138, v138
	v_lshlrev_b32_e32 v140, 16, v134
	v_and_b32_e32 v132, 0xffff0000, v132
	v_max_f32_e32 v130, 0x358637bd, v140
	v_max_f32_e32 v129, 0x358637bd, v129
	v_mul_f32_e32 v130, v130, v131
	v_max_f32_e32 v131, v132, v132
	v_cndmask_b32_e64 v132, v138, 1.0, s[20:21]
	v_rcp_f32_e32 v138, v129
	v_and_b32_e32 v134, 0xffff0000, v134
	v_max_f32_e32 v131, 0x358637bd, v131
	v_mul_f32_e32 v129, v131, v132
	v_max_f32_e32 v131, v134, v134
	v_max_f32_e32 v134, 0x358637bd, v144
	v_lshlrev_b32_e32 v139, 16, v133
	v_max_f32_e32 v131, 0x358637bd, v131
	v_cndmask_b32_e64 v132, v138, 1.0, s[20:21]
	v_rcp_f32_e32 v134, v134
	v_mul_f32_e32 v131, v131, v132
	v_max_f32_e32 v132, v139, v139
	v_max_f32_e32 v138, 0x358637bd, v146
	v_rcp_f32_e32 v138, v138
	v_max_f32_e32 v139, 0x358637bd, v145
	v_rcp_f32_e32 v139, v139
	v_lshlrev_b32_e32 v141, 16, v135
	v_max_f32_e32 v132, 0x358637bd, v132
	v_cndmask_b32_e64 v134, v134, 1.0, s[20:21]
	v_mul_f32_e32 v132, v132, v134
	v_max_f32_e32 v134, 0x358637bd, v141
	v_cndmask_b32_e64 v138, v138, 1.0, s[20:21]
	v_mul_f32_e32 v134, v134, v138
	v_cndmask_b32_e64 v138, v139, 1.0, s[20:21]
	v_max_f32_e32 v139, 0x358637bd, v142
	v_rcp_f32_e32 v139, v139
	v_and_b32_e32 v133, 0xffff0000, v133
	v_and_b32_e32 v135, 0xffff0000, v135
	v_max_f32_e32 v133, 0x358637bd, v133
	v_mul_f32_e32 v133, v133, v138
	v_max_f32_e32 v135, 0x358637bd, v135
	v_cndmask_b32_e64 v138, v139, 1.0, s[20:21]
	v_mul_f32_e32 v135, v135, v138
	v_pk_mul_f32 v[6:7], v[6:7], v[132:133]
	v_pk_mul_f32 v[4:5], v[4:5], v[128:129]
	v_pk_mul_f32 v[2:3], v[2:3], v[134:135]
	s_and_b64 vcc, exec, s[4:5]
	v_pk_mul_f32 v[0:1], v[0:1], v[130:131]
	s_cbranch_vccnz .LBB0_856
	v_cvt_pk_bf16_f32 v128, v4, v5
	v_cvt_pk_bf16_f32 v129, v6, v7
	v_cvt_pk_bf16_f32 v130, v0, v1
	v_cvt_pk_bf16_f32 v131, v2, v3
	global_store_dwordx4 v[136:137], v[128:131], off offset:256
